# stack2 + rows loop software prefetch: next iteration's first row loaded into spare registers during the second row's processing; unneeded waits relaxed to vmcnt(4)
# speedup vs baseline: 1.0095x; 1.0095x over previous
; __device__ __forceinline__ void phase_rows(const Ctx& c, int l) {
;     ...
;     for (int m0 = gw; m0 < MTOK; m0 += 2 * NGW) {
;         f32x4 v[2][4];
; #pragma unroll
;         for (int q = 0; q < 2; ++q) { const int mr = min(m0 + q * NGW, MTOK - 1); const f32x4* xr = (const f32x4*)(src + (size_t)mr * DM) + lane;
; #pragma unroll
;             for (int j = 0; j < 4; ++j) v[q][j] = xr[64 * j]; }
.Lrows_lds_skip:
	s_ashr_i32 s47, s46, 31
	s_lshl_b64 s[16:17], s[46:47], 12
	v_lshl_add_u64 v[210:211], v[174:175], 0, s[16:17]
	global_load_dwordx4 v[238:241], v[210:211], off nt
	global_load_dwordx4 v[242:245], v[210:211], off offset:1024 nt
	global_load_dwordx4 v[246:249], v[210:211], off offset:2048 nt
	global_load_dwordx4 v[206:209], v[210:211], off offset:3072 nt
	s_branch .LBB0_487

; __device__ __forceinline__ void phase_rows(const Ctx& c, int l) {
;     ...
;     for (int m0 = gw; m0 < MTOK; m0 += 2 * NGW) {
;         f32x4 v[2][4];
; #pragma unroll
;         for (int q = 0; q < 2; ++q) { const int mr = min(m0 + q * NGW, MTOK - 1); const f32x4* xr = (const f32x4*)(src + (size_t)mr * DM) + lane;
; #pragma unroll
;             for (int j = 0; j < 4; ++j) v[q][j] = xr[64 * j]; }
; #pragma unroll
;         for (int q = 0; q < 2; ++q) {
;         const int m = m0 + q * NGW;
;         if (m >= MTOK) continue;
;         if (l > 0) {
;             float s = 0.f;
; #pragma unroll
;             for (int j = 0; j < 4; ++j) s += (v[q][j].x + v[q][j].y) + (v[q][j].z + v[q][j].w);
;             const float mean = wave_sum(s) * (1.f / DM); float s2 = 0.f;
; #pragma unroll
;             for (int j = 0; j < 4; ++j) { v[q][j] = v[q][j] - mean; s2 += (v[q][j].x * v[q][j].x + v[q][j].y * v[q][j].y) + (v[q][j].z * v[q][j].z + v[q][j].w * v[q][j].w); }
;             const float rstd = 1.f / sqrtf(wave_sum(s2) * (1.f / DM) + LN_EPS);
;             const f32x4* gp = (const f32x4*)(c.inp(IN_LNG) + (size_t)(l - 1) * DM) + lane; const f32x4* bp = (const f32x4*)(c.inp(IN_LNB) + (size_t)(l - 1) * DM) + lane;
;             f32x4* orow = (f32x4*)(c.out + (size_t)m * DM) + lane;
; #pragma unroll
;             for (int j = 0; j < 4; ++j) { v[q][j] = v[q][j] * rstd * gp[64 * j] + bp[64 * j]; if (l == NLAYER) orow[64 * j] = v[q][j]; }
;             if (l < NLAYER && lane == 0) *(float2*)((float*)(c.ws + WS_STATS) + (size_t)m * 2) = make_float2(mean, rstd);
.LBB0_487:
	s_add_i32 s54, s46, s26
	s_ashr_i32 s47, s46, 31
	s_min_i32 s16, s54, 0x7fff
	s_lshl_b64 s[60:61], s[46:47], 12
	s_ashr_i32 s17, s16, 31
	s_waitcnt vmcnt(0)
	v_lshl_add_u64 v[138:139], v[174:175], 0, s[60:61]
	s_lshl_b64 s[16:17], s[16:17], 12
	v_mov_b64_e32 v[166:167], v[238:239]
	v_mov_b64_e32 v[168:169], v[240:241]
	v_mov_b64_e32 v[162:163], v[242:243]
	v_mov_b64_e32 v[164:165], v[244:245]
	v_mov_b64_e32 v[158:159], v[246:247]
	v_mov_b64_e32 v[160:161], v[248:249]
	v_mov_b64_e32 v[154:155], v[206:207]
	v_mov_b64_e32 v[156:157], v[208:209]
	v_lshl_add_u64 v[138:139], v[174:175], 0, s[16:17]
	global_load_dwordx4 v[150:153], v[138:139], off nt
	global_load_dwordx4 v[146:149], v[138:139], off offset:1024 nt
	global_load_dwordx4 v[142:145], v[138:139], off offset:2048 nt
	s_nop 0
	global_load_dwordx4 v[138:141], v[138:139], off offset:3072 nt
	v_cndmask_b32_e64 v96, 0, 1, s[48:49]
	v_cmp_ne_u32_e64 s[42:43], 1, v96
	s_andn2_b64 vcc, exec, s[48:49]
	s_cbranch_vccnz .LBB0_500
	s_waitcnt vmcnt(4)
	v_mov_b32_e32 v170, v167
	v_mov_b32_e32 v171, v168
	v_mov_b32_e32 v172, v166
	v_mov_b32_e32 v173, v169
	v_pk_add_f32 v[170:171], v[170:171], v[172:173]
	v_mov_b32_e32 v172, v163
	v_mov_b32_e32 v173, v164
	v_mov_b32_e32 v180, v162
	v_mov_b32_e32 v181, v165
	v_pk_add_f32 v[172:173], v[172:173], v[180:181]
	v_add_f32_e32 v96, v170, v171
	v_pk_add_f32 v[172:173], v[172:173], v[172:173] op_sel:[0,1] op_sel_hi:[1,0]
	v_add_f32_e32 v170, 0, v96
	v_add_f32_e32 v180, v158, v159
	v_add_f32_e32 v182, v160, v161
	v_mov_b32_e32 v171, v154
	v_mov_b32_e32 v173, v155
	v_mov_b32_e32 v181, v156
	v_mov_b32_e32 v183, v157
	v_pk_add_f32 v[170:171], v[170:171], v[172:173]
	v_pk_add_f32 v[172:173], v[180:181], v[182:183]
	s_load_dwordx4 s[64:67], s[12:13], 0x98
	v_pk_add_f32 v[170:171], v[170:171], v[172:173]
	v_lshl_add_u64 v[184:185], v[178:179], 0, s[60:61]
	v_add_f32_e32 v96, v170, v171
	s_nop 1
	v_add_f32_dpp v96, v96, v96 quad_perm:[1,0,3,2] row_mask:0xf bank_mask:0xf bound_ctrl:1
	s_nop 1
	v_add_f32_dpp v96, v96, v96 quad_perm:[2,3,0,1] row_mask:0xf bank_mask:0xf bound_ctrl:1
	s_nop 1
	v_add_f32_dpp v96, v96, v96 row_half_mirror row_mask:0xf bank_mask:0xf bound_ctrl:1
	s_nop 1
	v_add_f32_dpp v96, v96, v96 row_mirror row_mask:0xf bank_mask:0xf bound_ctrl:1
	s_nop 0
	v_readlane_b32 s0, v96, 16
	v_readlane_b32 s6, v96, 48
	v_readlane_b32 s16, v96, 0
	v_readlane_b32 s17, v96, 32
	v_mov_b32_e32 v170, s0
	v_mov_b32_e32 v171, s6
	v_pk_add_f32 v[170:171], s[16:17], v[170:171]
	s_nop 0
	v_add_f32_e32 v96, v170, v171
	v_fmamk_f32 v167, v96, 0xba800000, v167
	v_fmamk_f32 v166, v96, 0xba800000, v166
	v_fmamk_f32 v169, v96, 0xba800000, v169
	v_fmac_f32_e32 v168, 0xba800000, v96
	v_pk_mul_f32 v[170:171], v[168:169], v[168:169]
	v_pk_mul_f32 v[172:173], v[166:167], v[166:167]
	v_fmamk_f32 v183, v96, 0xba800000, v165
	v_pk_mov_b32 v[180:181], v[172:173], v[170:171] op_sel:[1,0]
	v_mov_b32_e32 v173, v171
	v_fmamk_f32 v182, v96, 0xba800000, v164
	v_fmamk_f32 v163, v96, 0xba800000, v163
	v_fmac_f32_e32 v162, 0xba800000, v96
	v_pk_add_f32 v[170:171], v[180:181], v[172:173]
	v_pk_mul_f32 v[164:165], v[182:183], v[182:183]
	v_pk_mul_f32 v[172:173], v[162:163], v[162:163]
	v_fmac_f32_e32 v158, 0xba800000, v96
	v_pk_mov_b32 v[180:181], v[172:173], v[164:165] op_sel:[1,0]
	v_mov_b32_e32 v173, v165
	v_pk_add_f32 v[164:165], v[180:181], v[172:173]
	v_fmamk_f32 v160, v96, 0xba800000, v160
	v_pk_add_f32 v[164:165], v[164:165], v[164:165] op_sel_hi:[0,1]
	v_fmamk_f32 v159, v96, 0xba800000, v159
	v_mul_f32_e32 v164, v158, v158
	v_fmamk_f32 v161, v96, 0xba800000, v161
	v_pk_fma_f32 v[172:173], v[158:159], v[158:159], v[164:165] op_sel_hi:[1,1,0]
	v_mul_f32_e32 v164, v160, v160
	v_pk_add_f32 v[170:171], v[170:171], v[170:171] op_sel_hi:[0,1]
	v_pk_fma_f32 v[180:181], v[160:161], v[160:161], v[164:165] op_sel_hi:[1,1,0]
	v_fmamk_f32 v157, v96, 0xba800000, v157
	v_fmamk_f32 v156, v96, 0xba800000, v156
	v_fmamk_f32 v155, v96, 0xba800000, v155
	v_fmac_f32_e32 v154, 0xba800000, v96
	v_mul_f32_e32 v172, v154, v154
	v_mul_f32_e32 v180, v155, v155
	v_mul_f32_e32 v170, v156, v156
	v_mul_f32_e32 v164, v157, v157
	v_pk_add_f32 v[172:173], v[172:173], v[180:181]
	v_pk_add_f32 v[164:165], v[170:171], v[164:165]
	s_nop 0
	v_pk_add_f32 v[164:165], v[172:173], v[164:165]
	s_nop 0
	v_add_f32_e32 v164, v164, v165
	s_nop 1
	v_add_f32_dpp v164, v164, v164 quad_perm:[1,0,3,2] row_mask:0xf bank_mask:0xf bound_ctrl:1
	s_nop 1
	v_add_f32_dpp v164, v164, v164 quad_perm:[2,3,0,1] row_mask:0xf bank_mask:0xf bound_ctrl:1
	s_nop 1
	v_add_f32_dpp v164, v164, v164 row_half_mirror row_mask:0xf bank_mask:0xf bound_ctrl:1
	s_nop 1
	v_add_f32_dpp v164, v164, v164 row_mirror row_mask:0xf bank_mask:0xf bound_ctrl:1
	s_nop 0
	v_readlane_b32 s0, v164, 16
	v_readlane_b32 s6, v164, 48
	v_readlane_b32 s16, v164, 0
	v_readlane_b32 s17, v164, 32
	v_mov_b32_e32 v164, s0
	v_mov_b32_e32 v165, s6
	v_pk_add_f32 v[164:165], s[16:17], v[164:165]
	s_nop 0
	v_add_f32_e32 v164, v164, v165
	v_fmamk_f32 v164, v164, 0x3a800000, v219
	v_cmp_gt_f32_e32 vcc, s87, v164
	v_mul_f32_e32 v165, 0x4f800000, v164
	s_nop 0
	v_cndmask_b32_e32 v164, v164, v165, vcc
	v_sqrt_f32_e32 v165, v164
	s_nop 0
	v_add_u32_e32 v170, -1, v165
	v_fma_f32 v171, -v170, v165, v164
	v_cmp_ge_f32_e64 s[40:41], 0, v171
	v_add_u32_e32 v171, 1, v165
	s_nop 0
	v_cndmask_b32_e64 v170, v165, v170, s[40:41]
	v_fma_f32 v165, -v171, v165, v164
	v_cmp_lt_f32_e64 s[40:41], 0, v165
	s_nop 1
	v_cndmask_b32_e64 v165, v170, v171, s[40:41]
	v_mul_f32_e32 v170, 0x37800000, v165
	v_cndmask_b32_e32 v165, v165, v170, vcc
	v_cmp_class_f32_e32 vcc, v164, v213
	s_nop 1
	v_cndmask_b32_e32 v164, v165, v164, vcc
	v_div_scale_f32 v165, s[16:17], v164, v164, 1.0
	v_rcp_f32_e32 v170, v165
	s_lshl_b64 s[16:17], s[22:23], 2
	s_waitcnt lgkmcnt(0)
	s_add_u32 s20, s64, s16
	s_addc_u32 s21, s65, s17
	v_fma_f32 v171, -v165, v170, 1.0
	v_fmac_f32_e32 v170, v171, v170
	v_div_scale_f32 v171, vcc, 1.0, v164, 1.0
	v_mul_f32_e32 v172, v171, v170
	v_fma_f32 v173, -v165, v172, v171
	v_fmac_f32_e32 v172, v173, v170
	v_fma_f32 v165, -v165, v172, v171
	v_div_fmas_f32 v165, v165, v170, v172
	v_div_fixup_f32 v180, v165, v164, 1.0
	v_lshlrev_b64 v[164:165], 4, v[200:201]
	s_add_u32 s16, s66, s16
	v_lshl_add_u64 v[186:187], s[20:21], 0, v[164:165]
	s_addc_u32 s17, s67, s17
	v_lshl_add_u64 v[188:189], s[16:17], 0, v[164:165]
	v_pk_mul_f32 v[190:191], v[166:167], v[180:181] op_sel_hi:[1,0]
	ds_read_b128 v[164:167], v251
	ds_read_b128 v[170:173], v251 offset:4096
	v_pk_mul_f32 v[168:169], v[168:169], v[180:181] op_sel_hi:[1,0]
	s_andn2_b64 vcc, exec, s[50:51]
	s_waitcnt lgkmcnt(0)
	v_pk_fma_f32 v[168:169], v[166:167], v[168:169], v[172:173]
	v_pk_fma_f32 v[166:167], v[164:165], v[190:191], v[170:171]
	v_cndmask_b32_e64 v164, 0, 1, s[50:51]
	v_cmp_ne_u32_e64 s[40:41], 1, v164
	s_cbranch_vccnz .LBB0_490
	global_store_dwordx4 v[184:185], v[166:169], off

; __device__ __forceinline__ unsigned pk_bf16(float lo, float hi) { return pg8::cvt_pk_bf16(lo, hi); }
; __device__ __forceinline__ void phase_rows(const Ctx& c, int l) {
;     ...
;         if (l < NLAYER) {
;             u32x2* o8 = (u32x2*)(XB + (size_t)m * DM) + lane;
; #pragma unroll
;             for (int j = 0; j < 4; ++j) { u32x2 w; w.x = pk_bf16(v[q][j].x, v[q][j].y); w.y = pk_bf16(v[q][j].z, v[q][j].w); o8[64 * j] = w; }
;             f32x4 a0 = {0.f, 0.f, 0.f, 0.f}, a1 = {0.f, 0.f, 0.f, 0.f};
; #pragma unroll
;             for (int j = 0; j < 4; ++j)
; #pragma unroll
;                 for (int i = 0; i < 4; ++i) { const float xv = v[q][j][i]; a0 += wf[4 * j + i][0] * xv; a1 += wf[4 * j + i][1] * xv; }
.LBB0_501:
	s_lshl_b64 s[16:17], s[46:47], 11
	v_lshl_add_u64 v[170:171], v[176:177], 0, s[16:17]
	s_waitcnt vmcnt(4)
	v_cvt_pk_bf16_f32 v172, v166, v167
	v_cvt_pk_bf16_f32 v173, v168, v169
	global_store_dwordx2 v[170:171], v[172:173], off
	v_cvt_pk_bf16_f32 v172, v162, v163
	v_cvt_pk_bf16_f32 v173, v164, v165
	global_store_dwordx2 v[170:171], v[172:173], off offset:512
	v_cvt_pk_bf16_f32 v172, v158, v159
	v_cvt_pk_bf16_f32 v173, v160, v161
	global_store_dwordx2 v[170:171], v[172:173], off offset:1024
	v_cvt_pk_bf16_f32 v172, v154, v155
	v_cvt_pk_bf16_f32 v173, v156, v157
	global_store_dwordx2 v[170:171], v[172:173], off offset:1536
	v_pk_fma_f32 v[170:171], v[0:1], v[166:167], 0 op_sel_hi:[1,0,0]
	v_pk_fma_f32 v[172:173], v[2:3], v[166:167], 0 op_sel_hi:[1,0,0]
	v_pk_fma_f32 v[180:181], v[4:5], v[166:167], 0 op_sel_hi:[1,0,0]
	v_pk_fma_f32 v[182:183], v[6:7], v[166:167], 0 op_sel_hi:[1,0,0]
	v_pk_fma_f32 v[170:171], v[12:13], v[166:167], v[170:171] op_sel:[0,1,0]
	v_pk_fma_f32 v[172:173], v[14:15], v[166:167], v[172:173] op_sel:[0,1,0]
	v_pk_fma_f32 v[182:183], v[10:11], v[166:167], v[182:183] op_sel:[0,1,0]
	v_pk_fma_f32 v[166:167], v[8:9], v[166:167], v[180:181] op_sel:[0,1,0]
	v_pk_fma_f32 v[170:171], v[20:21], v[168:169], v[170:171] op_sel_hi:[1,0,1]
	v_mov_b32_e32 v96, v169
	v_pk_fma_f32 v[172:173], v[22:23], v[168:169], v[172:173] op_sel_hi:[1,0,1]
	v_pk_fma_f32 v[166:167], v[16:17], v[168:169], v[166:167] op_sel_hi:[1,0,1]
	v_pk_fma_f32 v[180:181], v[18:19], v[168:169], v[182:183] op_sel_hi:[1,0,1]
	v_pk_fma_f32 v[170:171], v[28:29], v[96:97], v[170:171] op_sel_hi:[1,0,1]
	v_pk_fma_f32 v[168:169], v[30:31], v[96:97], v[172:173] op_sel_hi:[1,0,1]
	v_pk_fma_f32 v[172:173], v[26:27], v[96:97], v[180:181] op_sel_hi:[1,0,1]
	v_pk_fma_f32 v[166:167], v[24:25], v[96:97], v[166:167] op_sel_hi:[1,0,1]
	v_pk_fma_f32 v[170:171], v[36:37], v[162:163], v[170:171] op_sel_hi:[1,0,1]
	v_pk_fma_f32 v[168:169], v[38:39], v[162:163], v[168:169] op_sel_hi:[1,0,1]
	v_pk_fma_f32 v[166:167], v[32:33], v[162:163], v[166:167] op_sel_hi:[1,0,1]
	v_pk_fma_f32 v[172:173], v[34:35], v[162:163], v[172:173] op_sel_hi:[1,0,1]
	v_pk_fma_f32 v[170:171], v[44:45], v[162:163], v[170:171] op_sel:[0,1,0]
	v_pk_fma_f32 v[168:169], v[46:47], v[162:163], v[168:169] op_sel:[0,1,0]
	v_pk_fma_f32 v[172:173], v[42:43], v[162:163], v[172:173] op_sel:[0,1,0]
	v_pk_fma_f32 v[162:163], v[40:41], v[162:163], v[166:167] op_sel:[0,1,0]
	v_pk_fma_f32 v[166:167], v[52:53], v[164:165], v[170:171] op_sel_hi:[1,0,1]
	v_mov_b32_e32 v96, v165
	v_pk_fma_f32 v[168:169], v[54:55], v[164:165], v[168:169] op_sel_hi:[1,0,1]
	v_pk_fma_f32 v[162:163], v[48:49], v[164:165], v[162:163] op_sel_hi:[1,0,1]
	v_pk_fma_f32 v[170:171], v[50:51], v[164:165], v[172:173] op_sel_hi:[1,0,1]
	v_pk_fma_f32 v[166:167], v[60:61], v[96:97], v[166:167] op_sel_hi:[1,0,1]
	v_pk_fma_f32 v[164:165], v[62:63], v[96:97], v[168:169] op_sel_hi:[1,0,1]
	v_pk_fma_f32 v[168:169], v[58:59], v[96:97], v[170:171] op_sel_hi:[1,0,1]
	v_pk_fma_f32 v[162:163], v[56:57], v[96:97], v[162:163] op_sel_hi:[1,0,1]
	v_pk_fma_f32 v[166:167], v[68:69], v[158:159], v[166:167] op_sel_hi:[1,0,1]
	v_pk_fma_f32 v[164:165], v[70:71], v[158:159], v[164:165] op_sel_hi:[1,0,1]
	v_pk_fma_f32 v[162:163], v[64:65], v[158:159], v[162:163] op_sel_hi:[1,0,1]
	v_pk_fma_f32 v[168:169], v[66:67], v[158:159], v[168:169] op_sel_hi:[1,0,1]
	v_pk_fma_f32 v[166:167], v[76:77], v[158:159], v[166:167] op_sel:[0,1,0]
	v_pk_fma_f32 v[164:165], v[78:79], v[158:159], v[164:165] op_sel:[0,1,0]
	v_pk_fma_f32 v[168:169], v[74:75], v[158:159], v[168:169] op_sel:[0,1,0]
	v_pk_fma_f32 v[158:159], v[72:73], v[158:159], v[162:163] op_sel:[0,1,0]
	v_pk_fma_f32 v[162:163], v[92:93], v[160:161], v[166:167] op_sel_hi:[1,0,1]
	v_mov_b32_e32 v96, v161
	v_pk_fma_f32 v[164:165], v[94:95], v[160:161], v[164:165] op_sel_hi:[1,0,1]
	v_pk_fma_f32 v[158:159], v[88:89], v[160:161], v[158:159] op_sel_hi:[1,0,1]
	v_pk_fma_f32 v[166:167], v[90:91], v[160:161], v[168:169] op_sel_hi:[1,0,1]
	v_pk_fma_f32 v[162:163], v[102:103], v[96:97], v[162:163] op_sel_hi:[1,0,1]
	v_pk_fma_f32 v[160:161], v[104:105], v[96:97], v[164:165] op_sel_hi:[1,0,1]
	v_pk_fma_f32 v[164:165], v[100:101], v[96:97], v[166:167] op_sel_hi:[1,0,1]
	v_pk_fma_f32 v[158:159], v[98:99], v[96:97], v[158:159] op_sel_hi:[1,0,1]
	v_pk_fma_f32 v[162:163], v[110:111], v[154:155], v[162:163] op_sel_hi:[1,0,1]
	v_pk_fma_f32 v[160:161], v[112:113], v[154:155], v[160:161] op_sel_hi:[1,0,1]
	v_pk_fma_f32 v[158:159], v[106:107], v[154:155], v[158:159] op_sel_hi:[1,0,1]
	v_pk_fma_f32 v[164:165], v[108:109], v[154:155], v[164:165] op_sel_hi:[1,0,1]
	v_pk_fma_f32 v[162:163], v[118:119], v[154:155], v[162:163] op_sel:[0,1,0]
	v_pk_fma_f32 v[160:161], v[120:121], v[154:155], v[160:161] op_sel:[0,1,0]
	v_pk_fma_f32 v[164:165], v[116:117], v[154:155], v[164:165] op_sel:[0,1,0]
	v_pk_fma_f32 v[154:155], v[114:115], v[154:155], v[158:159] op_sel:[0,1,0]
	v_pk_fma_f32 v[158:159], v[126:127], v[156:157], v[162:163] op_sel_hi:[1,0,1]
	v_mov_b32_e32 v96, v157
	v_pk_fma_f32 v[160:161], v[128:129], v[156:157], v[160:161] op_sel_hi:[1,0,1]
	v_pk_fma_f32 v[154:155], v[122:123], v[156:157], v[154:155] op_sel_hi:[1,0,1]
	v_pk_fma_f32 v[162:163], v[124:125], v[156:157], v[164:165] op_sel_hi:[1,0,1]
	v_pk_fma_f32 v[158:159], v[134:135], v[96:97], v[158:159] op_sel_hi:[1,0,1]
	v_pk_fma_f32 v[156:157], v[136:137], v[96:97], v[160:161] op_sel_hi:[1,0,1]
	v_pk_fma_f32 v[160:161], v[132:133], v[96:97], v[162:163] op_sel_hi:[1,0,1]
; __device__ __forceinline__ void phase_rows(const Ctx& c, int l) {
;     ...
;             float f[8];
; #pragma unroll
;             for (int h = 0; h < 4; ++h) { f[h] = wave_sum(a0[h]) + bfv[h]; f[4 + h] = wave_sum(a1[h]) + bfv[4 + h]; }
;             if (lane == 0) { *(f32x4*)(flog + (size_t)m * 8) = (f32x4){f[0], f[1], f[2], f[3]}; *(f32x4*)(flog + (size_t)m * 8 + 4) = (f32x4){f[4], f[5], f[6], f[7]}; }
	v_pk_fma_f32 v[154:155], v[130:131], v[96:97], v[154:155] op_sel_hi:[1,0,1]
	v_add_f32_dpp v96, v158, v158 quad_perm:[1,0,3,2] row_mask:0xf bank_mask:0xf bound_ctrl:1
	s_nop 1
	v_add_f32_dpp v96, v96, v96 quad_perm:[2,3,0,1] row_mask:0xf bank_mask:0xf bound_ctrl:1
	s_nop 1
	v_add_f32_dpp v96, v96, v96 row_half_mirror row_mask:0xf bank_mask:0xf bound_ctrl:1
	s_nop 1
	v_add_f32_dpp v96, v96, v96 row_mirror row_mask:0xf bank_mask:0xf bound_ctrl:1
	s_nop 0
	v_readlane_b32 s68, v96, 0
	v_readlane_b32 s21, v96, 16
	v_readlane_b32 s64, v96, 32
	v_readlane_b32 s17, v96, 48
	v_add_f32_dpp v96, v154, v154 quad_perm:[1,0,3,2] row_mask:0xf bank_mask:0xf bound_ctrl:1
	s_nop 1
	v_add_f32_dpp v96, v96, v96 quad_perm:[2,3,0,1] row_mask:0xf bank_mask:0xf bound_ctrl:1
	s_nop 1
	v_add_f32_dpp v96, v96, v96 row_half_mirror row_mask:0xf bank_mask:0xf bound_ctrl:1
	s_nop 1
	v_add_f32_dpp v96, v96, v96 row_mirror row_mask:0xf bank_mask:0xf bound_ctrl:1
	s_nop 0
	v_readlane_b32 s62, v96, 0
	v_readlane_b32 s6, v96, 16
	v_readlane_b32 s60, v96, 32
	v_readlane_b32 s0, v96, 48
	v_add_f32_dpp v96, v159, v159 quad_perm:[1,0,3,2] row_mask:0xf bank_mask:0xf bound_ctrl:1
	s_nop 1
	v_add_f32_dpp v96, v96, v96 quad_perm:[2,3,0,1] row_mask:0xf bank_mask:0xf bound_ctrl:1
	s_nop 1
	v_add_f32_dpp v96, v96, v96 row_half_mirror row_mask:0xf bank_mask:0xf bound_ctrl:1
	s_nop 1
	v_add_f32_dpp v96, v96, v96 row_mirror row_mask:0xf bank_mask:0xf bound_ctrl:1
	s_nop 0
	v_readlane_b32 s69, v96, 0
	v_readlane_b32 s55, v96, 16
	v_readlane_b32 s65, v96, 32
	v_readlane_b32 s34, v96, 48
	v_add_f32_dpp v96, v155, v155 quad_perm:[1,0,3,2] row_mask:0xf bank_mask:0xf bound_ctrl:1
	s_nop 1
	v_add_f32_dpp v96, v96, v96 quad_perm:[2,3,0,1] row_mask:0xf bank_mask:0xf bound_ctrl:1
	s_nop 1
	v_add_f32_dpp v96, v96, v96 row_half_mirror row_mask:0xf bank_mask:0xf bound_ctrl:1
	s_nop 1
	v_add_f32_dpp v96, v96, v96 row_mirror row_mask:0xf bank_mask:0xf bound_ctrl:1
	s_nop 0
	v_readlane_b32 s63, v96, 0
	v_readlane_b32 s20, v96, 16
	v_readlane_b32 s61, v96, 32
	v_readlane_b32 s16, v96, 48
	v_add_f32_dpp v96, v156, v156 quad_perm:[1,0,3,2] row_mask:0xf bank_mask:0xf bound_ctrl:1
	s_nop 1
	v_add_f32_dpp v96, v96, v96 quad_perm:[2,3,0,1] row_mask:0xf bank_mask:0xf bound_ctrl:1
	s_nop 1
	v_add_f32_dpp v96, v96, v96 row_half_mirror row_mask:0xf bank_mask:0xf bound_ctrl:1
	s_nop 1
	v_add_f32_dpp v96, v96, v96 row_mirror row_mask:0xf bank_mask:0xf bound_ctrl:1
	s_nop 0
	v_readlane_b32 s92, v96, 0
	v_readlane_b32 s87, v96, 16
	v_readlane_b32 s74, v96, 32
	v_readlane_b32 s81, v96, 48
	v_add_f32_dpp v96, v160, v160 quad_perm:[1,0,3,2] row_mask:0xf bank_mask:0xf bound_ctrl:1
	s_nop 1
	v_add_f32_dpp v96, v96, v96 quad_perm:[2,3,0,1] row_mask:0xf bank_mask:0xf bound_ctrl:1
	s_nop 1
	v_add_f32_dpp v96, v96, v96 row_half_mirror row_mask:0xf bank_mask:0xf bound_ctrl:1
	s_nop 1
	v_add_f32_dpp v96, v96, v96 row_mirror row_mask:0xf bank_mask:0xf bound_ctrl:1
	s_nop 0
	v_readlane_b32 s72, v96, 0
	v_readlane_b32 s36, v96, 16
	v_readlane_b32 s70, v96, 32
	v_readlane_b32 s31, v96, 48
	v_add_f32_dpp v96, v157, v157 quad_perm:[1,0,3,2] row_mask:0xf bank_mask:0xf bound_ctrl:1
	s_nop 1
	v_add_f32_dpp v96, v96, v96 quad_perm:[2,3,0,1] row_mask:0xf bank_mask:0xf bound_ctrl:1
	s_nop 1
	v_add_f32_dpp v96, v96, v96 row_half_mirror row_mask:0xf bank_mask:0xf bound_ctrl:1
	s_nop 1
	v_add_f32_dpp v96, v96, v96 row_mirror row_mask:0xf bank_mask:0xf bound_ctrl:1
	s_nop 0
	v_readlane_b32 s93, v96, 0
	v_readlane_b32 vcc_lo, v96, 16
	v_readlane_b32 s75, v96, 32
	v_readlane_b32 s94, v96, 48
	v_add_f32_dpp v96, v161, v161 quad_perm:[1,0,3,2] row_mask:0xf bank_mask:0xf bound_ctrl:1
	s_nop 1
	v_add_f32_dpp v96, v96, v96 quad_perm:[2,3,0,1] row_mask:0xf bank_mask:0xf bound_ctrl:1
	s_nop 1
	v_add_f32_dpp v96, v96, v96 row_half_mirror row_mask:0xf bank_mask:0xf bound_ctrl:1
	s_nop 1
	v_add_f32_dpp v96, v96, v96 row_mirror row_mask:0xf bank_mask:0xf bound_ctrl:1
	s_nop 0
	v_readlane_b32 s73, v96, 0
	v_readlane_b32 s86, v96, 16
	v_readlane_b32 s71, v96, 32
	v_readlane_b32 s80, v96, 48
	s_and_saveexec_b64 s[66:67], s[38:39]
	s_cbranch_execz .LBB0_503
	v_mov_b32_e32 v154, s87
	v_mov_b32_e32 v155, vcc_lo
	v_mov_b32_e32 v156, s21
	v_mov_b32_e32 v157, s55
	v_mov_b32_e32 v158, s81
	v_mov_b32_e32 v159, s94
	v_mov_b32_e32 v160, s17
	v_mov_b32_e32 v161, s34
	v_pk_add_f32 v[154:155], s[92:93], v[154:155]
	v_pk_add_f32 v[156:157], s[68:69], v[156:157]
	v_pk_add_f32 v[158:159], s[74:75], v[158:159]
	v_pk_add_f32 v[160:161], s[64:65], v[160:161]
	v_pk_add_f32 v[154:155], v[154:155], v[158:159]
	v_pk_add_f32 v[160:161], v[156:157], v[160:161]
	v_pk_add_f32 v[156:157], v[86:87], v[154:155]
	v_pk_add_f32 v[154:155], v[84:85], v[160:161]
	v_mov_b32_e32 v158, s36
	v_mov_b32_e32 v159, s86
	v_mov_b32_e32 v160, s6
	v_mov_b32_e32 v161, s20
	v_mov_b32_e32 v162, s31
	v_mov_b32_e32 v163, s80
	v_mov_b32_e32 v164, s0
	v_mov_b32_e32 v165, s16
	s_lshl_b64 s[16:17], s[46:47], 5
	v_readlane_b32 s0, v253, 25
	v_pk_add_f32 v[158:159], s[72:73], v[158:159]
	v_pk_add_f32 v[160:161], s[62:63], v[160:161]
	v_pk_add_f32 v[162:163], s[70:71], v[162:163]
	v_pk_add_f32 v[164:165], s[60:61], v[164:165]
	s_add_u32 s16, s0, s16
	v_readlane_b32 s0, v253, 26
	v_pk_add_f32 v[164:165], v[160:161], v[164:165]
	v_pk_add_f32 v[158:159], v[158:159], v[162:163]
	s_addc_u32 s17, s0, s17
	v_pk_add_f32 v[160:161], v[82:83], v[158:159]
	v_pk_add_f32 v[158:159], v[80:81], v[164:165]
	global_store_dwordx4 v97, v[154:157], s[16:17]
	global_store_dwordx4 v97, v[158:161], s[16:17] offset:16

; __device__ __forceinline__ void phase_rows(const Ctx& c, int l) {
;     ...
;     for (int m0 = gw; m0 < MTOK; m0 += 2 * NGW) {
;         f32x4 v[2][4];
; #pragma unroll
;         for (int q = 0; q < 2; ++q) { const int mr = min(m0 + q * NGW, MTOK - 1); const f32x4* xr = (const f32x4*)(src + (size_t)mr * DM) + lane;
; #pragma unroll
;             for (int j = 0; j < 4; ++j) v[q][j] = xr[64 * j]; }
; #pragma unroll
;         for (int q = 0; q < 2; ++q) {
;         const int m = m0 + q * NGW;
;         if (m >= MTOK) continue;
;         if (l > 0) {
;             float s = 0.f;
; #pragma unroll
;             for (int j = 0; j < 4; ++j) s += (v[q][j].x + v[q][j].y) + (v[q][j].z + v[q][j].w);
;             const float mean = wave_sum(s) * (1.f / DM); float s2 = 0.f;
; #pragma unroll
;             for (int j = 0; j < 4; ++j) { v[q][j] = v[q][j] - mean; s2 += (v[q][j].x * v[q][j].x + v[q][j].y * v[q][j].y) + (v[q][j].z * v[q][j].z + v[q][j].w * v[q][j].w); }
;             const float rstd = 1.f / sqrtf(wave_sum(s2) * (1.f / DM) + LN_EPS);
;             const f32x4* gp = (const f32x4*)(c.inp(IN_LNG) + (size_t)(l - 1) * DM) + lane; const f32x4* bp = (const f32x4*)(c.inp(IN_LNB) + (size_t)(l - 1) * DM) + lane;
;             f32x4* orow = (f32x4*)(c.out + (size_t)m * DM) + lane;
; #pragma unroll
;             for (int j = 0; j < 4; ++j) { v[q][j] = v[q][j] * rstd * gp[64 * j] + bp[64 * j]; if (l == NLAYER) orow[64 * j] = v[q][j]; }
;             if (l < NLAYER && lane == 0) *(float2*)((float*)(c.ws + WS_STATS) + (size_t)m * 2) = make_float2(mean, rstd);
.LBB0_504:
	s_add_i32 s16, s54, s26
	s_min_i32 s16, s16, 0x7fff
	s_ashr_i32 s17, s16, 31
	s_lshl_b64 s[16:17], s[16:17], 12
	v_lshl_add_u64 v[210:211], v[174:175], 0, s[16:17]
	global_load_dwordx4 v[238:241], v[210:211], off nt
	global_load_dwordx4 v[242:245], v[210:211], off offset:1024 nt
	global_load_dwordx4 v[246:249], v[210:211], off offset:2048 nt
	global_load_dwordx4 v[206:209], v[210:211], off offset:3072 nt
	s_and_b64 vcc, exec, s[42:43]
	s_cbranch_vccnz .LBB0_516
	s_waitcnt vmcnt(4)
	v_mov_b32_e32 v154, v151
	v_mov_b32_e32 v155, v152
	v_mov_b32_e32 v156, v150
	v_mov_b32_e32 v157, v153
	v_pk_add_f32 v[154:155], v[154:155], v[156:157]
	v_mov_b32_e32 v156, v147
	v_mov_b32_e32 v157, v148
	v_mov_b32_e32 v158, v146
	v_mov_b32_e32 v159, v149
	v_pk_add_f32 v[156:157], v[156:157], v[158:159]
	v_add_f32_e32 v96, v154, v155
	v_pk_add_f32 v[156:157], v[156:157], v[156:157] op_sel:[0,1] op_sel_hi:[1,0]
	v_add_f32_e32 v154, 0, v96
	v_add_f32_e32 v158, v142, v143
	v_add_f32_e32 v160, v144, v145
	v_mov_b32_e32 v155, v138
	v_mov_b32_e32 v157, v139
	v_mov_b32_e32 v159, v140
	v_mov_b32_e32 v161, v141
	v_pk_add_f32 v[154:155], v[154:155], v[156:157]
	v_pk_add_f32 v[156:157], v[158:159], v[160:161]
	s_load_dwordx4 s[60:63], s[12:13], 0x98
	v_pk_add_f32 v[154:155], v[154:155], v[156:157]
	s_nop 0
	v_add_f32_e32 v96, v154, v155
	s_nop 1
	v_add_f32_dpp v96, v96, v96 quad_perm:[1,0,3,2] row_mask:0xf bank_mask:0xf bound_ctrl:1
	s_nop 1
	v_add_f32_dpp v96, v96, v96 quad_perm:[2,3,0,1] row_mask:0xf bank_mask:0xf bound_ctrl:1
	s_nop 1
	v_add_f32_dpp v96, v96, v96 row_half_mirror row_mask:0xf bank_mask:0xf bound_ctrl:1
	s_nop 1
	v_add_f32_dpp v96, v96, v96 row_mirror row_mask:0xf bank_mask:0xf bound_ctrl:1
	s_nop 0
	v_readlane_b32 s0, v96, 16
	v_readlane_b32 s6, v96, 48
	v_readlane_b32 s16, v96, 0
	v_readlane_b32 s17, v96, 32
	v_mov_b32_e32 v154, s0
	v_mov_b32_e32 v155, s6
	v_pk_add_f32 v[154:155], s[16:17], v[154:155]
	s_nop 0
	v_add_f32_e32 v96, v154, v155
	v_fmamk_f32 v151, v96, 0xba800000, v151
	v_fmamk_f32 v150, v96, 0xba800000, v150
	v_fmamk_f32 v153, v96, 0xba800000, v153
	v_fmac_f32_e32 v152, 0xba800000, v96
	v_pk_mul_f32 v[154:155], v[152:153], v[152:153]
	v_pk_mul_f32 v[156:157], v[150:151], v[150:151]
	v_fmamk_f32 v161, v96, 0xba800000, v149
	v_pk_mov_b32 v[158:159], v[156:157], v[154:155] op_sel:[1,0]
	v_mov_b32_e32 v157, v155
	v_fmamk_f32 v160, v96, 0xba800000, v148
	v_fmamk_f32 v147, v96, 0xba800000, v147
	v_fmac_f32_e32 v146, 0xba800000, v96
	v_pk_add_f32 v[154:155], v[158:159], v[156:157]
	v_pk_mul_f32 v[148:149], v[160:161], v[160:161]
	v_pk_mul_f32 v[156:157], v[146:147], v[146:147]
	v_fmac_f32_e32 v142, 0xba800000, v96
	v_pk_mov_b32 v[158:159], v[156:157], v[148:149] op_sel:[1,0]
	v_mov_b32_e32 v157, v149
	v_pk_add_f32 v[148:149], v[158:159], v[156:157]
	v_fmamk_f32 v144, v96, 0xba800000, v144
	v_pk_add_f32 v[148:149], v[148:149], v[148:149] op_sel_hi:[0,1]
	v_fmamk_f32 v143, v96, 0xba800000, v143
	v_mul_f32_e32 v148, v142, v142
	v_fmamk_f32 v145, v96, 0xba800000, v145
	v_pk_fma_f32 v[156:157], v[142:143], v[142:143], v[148:149] op_sel_hi:[1,1,0]
	v_mul_f32_e32 v148, v144, v144
	v_pk_add_f32 v[154:155], v[154:155], v[154:155] op_sel_hi:[0,1]
	v_pk_fma_f32 v[158:159], v[144:145], v[144:145], v[148:149] op_sel_hi:[1,1,0]
	v_fmamk_f32 v141, v96, 0xba800000, v141
	v_fmamk_f32 v140, v96, 0xba800000, v140
	v_fmamk_f32 v139, v96, 0xba800000, v139
	v_fmac_f32_e32 v138, 0xba800000, v96
	v_mul_f32_e32 v156, v138, v138
	v_mul_f32_e32 v158, v139, v139
	v_mul_f32_e32 v154, v140, v140
	v_mul_f32_e32 v148, v141, v141
	v_pk_add_f32 v[156:157], v[156:157], v[158:159]
	v_pk_add_f32 v[148:149], v[154:155], v[148:149]
	s_nop 0
	v_pk_add_f32 v[148:149], v[156:157], v[148:149]
	s_nop 0
	v_add_f32_e32 v148, v148, v149
	s_nop 1
	v_add_f32_dpp v148, v148, v148 quad_perm:[1,0,3,2] row_mask:0xf bank_mask:0xf bound_ctrl:1
	s_nop 1
	v_add_f32_dpp v148, v148, v148 quad_perm:[2,3,0,1] row_mask:0xf bank_mask:0xf bound_ctrl:1
	s_nop 1
	v_add_f32_dpp v148, v148, v148 row_half_mirror row_mask:0xf bank_mask:0xf bound_ctrl:1
	s_nop 1
	v_add_f32_dpp v148, v148, v148 row_mirror row_mask:0xf bank_mask:0xf bound_ctrl:1
	s_nop 0
	v_readlane_b32 s0, v148, 16
	v_readlane_b32 s6, v148, 48
	v_readlane_b32 s16, v148, 0
	v_readlane_b32 s17, v148, 32
	v_mov_b32_e32 v148, s0
	v_mov_b32_e32 v149, s6
	v_pk_add_f32 v[148:149], s[16:17], v[148:149]
	s_nop 0
	v_add_f32_e32 v148, v148, v149
	v_fmamk_f32 v148, v148, 0x3a800000, v219
	v_cmp_gt_f32_e32 vcc, s87, v148
	v_mul_f32_e32 v149, 0x4f800000, v148
	s_nop 0
	v_cndmask_b32_e32 v148, v148, v149, vcc
	v_sqrt_f32_e32 v149, v148
	s_nop 0
	v_add_u32_e32 v154, -1, v149
	v_fma_f32 v155, -v154, v149, v148
	v_cmp_ge_f32_e64 s[42:43], 0, v155
	v_add_u32_e32 v155, 1, v149
	s_nop 0
	v_cndmask_b32_e64 v154, v149, v154, s[42:43]
	v_fma_f32 v149, -v155, v149, v148
	v_cmp_lt_f32_e64 s[42:43], 0, v149
	s_nop 1
	v_cndmask_b32_e64 v149, v154, v155, s[42:43]
	v_mul_f32_e32 v154, 0x37800000, v149
	v_cndmask_b32_e32 v149, v149, v154, vcc
	v_cmp_class_f32_e32 vcc, v148, v213
	s_nop 1
	v_cndmask_b32_e32 v148, v149, v148, vcc
	v_div_scale_f32 v149, s[16:17], v148, v148, 1.0
	v_rcp_f32_e32 v154, v149
	s_lshl_b64 s[16:17], s[22:23], 2
	s_waitcnt lgkmcnt(0)
	s_add_u32 s20, s60, s16
	s_addc_u32 s21, s61, s17
	v_fma_f32 v155, -v149, v154, 1.0
	v_fmac_f32_e32 v154, v155, v154
	v_div_scale_f32 v155, vcc, 1.0, v148, 1.0
	v_mul_f32_e32 v156, v155, v154
	v_fma_f32 v157, -v149, v156, v155
	v_fmac_f32_e32 v156, v157, v154
	v_fma_f32 v149, -v149, v156, v155
	v_div_fmas_f32 v149, v149, v154, v156
	v_div_fixup_f32 v158, v149, v148, 1.0
	v_lshlrev_b64 v[148:149], 4, v[200:201]
	s_add_u32 s16, s62, s16
	v_lshl_add_u64 v[164:165], s[20:21], 0, v[148:149]
	s_addc_u32 s17, s63, s17
	v_lshl_add_u64 v[166:167], s[16:17], 0, v[148:149]
	v_pk_mul_f32 v[168:169], v[150:151], v[158:159] op_sel_hi:[1,0]
	ds_read_b128 v[148:151], v251
	ds_read_b128 v[154:157], v251 offset:4096
	s_ashr_i32 s55, s54, 31
	v_pk_mul_f32 v[152:153], v[152:153], v[158:159] op_sel_hi:[1,0]
	s_lshl_b64 s[16:17], s[54:55], 12
	v_lshl_add_u64 v[162:163], v[178:179], 0, s[16:17]
	s_andn2_b64 vcc, exec, s[50:51]
	s_waitcnt lgkmcnt(0)
	v_pk_fma_f32 v[152:153], v[150:151], v[152:153], v[156:157]
	v_pk_fma_f32 v[150:151], v[148:149], v[168:169], v[154:155]
	v_cndmask_b32_e64 v148, 0, 1, s[50:51]
	v_cmp_ne_u32_e64 s[42:43], 1, v148
	s_cbranch_vccnz .LBB0_507
	global_store_dwordx4 v[162:163], v[150:153], off

; __device__ __forceinline__ unsigned pk_bf16(float lo, float hi) { return pg8::cvt_pk_bf16(lo, hi); }
; __device__ __forceinline__ void phase_rows(const Ctx& c, int l) {
;     ...
;         if (l < NLAYER) {
;             u32x2* o8 = (u32x2*)(XB + (size_t)m * DM) + lane;
; #pragma unroll
;             for (int j = 0; j < 4; ++j) { u32x2 w; w.x = pk_bf16(v[q][j].x, v[q][j].y); w.y = pk_bf16(v[q][j].z, v[q][j].w); o8[64 * j] = w; }
;             f32x4 a0 = {0.f, 0.f, 0.f, 0.f}, a1 = {0.f, 0.f, 0.f, 0.f};
; #pragma unroll
;             for (int j = 0; j < 4; ++j)
; #pragma unroll
;                 for (int i = 0; i < 4; ++i) { const float xv = v[q][j][i]; a0 += wf[4 * j + i][0] * xv; a1 += wf[4 * j + i][1] * xv; }
.LBB0_516:
	s_and_b64 vcc, exec, s[40:41]
	s_cbranch_vccnz .LBB0_486
	s_ashr_i32 s55, s54, 31
	s_lshl_b64 s[16:17], s[54:55], 11
	s_waitcnt vmcnt(4)
	v_lshl_add_u64 v[154:155], v[176:177], 0, s[16:17]
	v_cvt_pk_bf16_f32 v156, v150, v151
	v_cvt_pk_bf16_f32 v157, v152, v153
	global_store_dwordx2 v[154:155], v[156:157], off
	v_cvt_pk_bf16_f32 v156, v146, v147
	v_cvt_pk_bf16_f32 v157, v148, v149
	global_store_dwordx2 v[154:155], v[156:157], off offset:512
	v_cvt_pk_bf16_f32 v156, v142, v143
	v_cvt_pk_bf16_f32 v157, v144, v145
	global_store_dwordx2 v[154:155], v[156:157], off offset:1024
	v_cvt_pk_bf16_f32 v156, v138, v139
	v_cvt_pk_bf16_f32 v157, v140, v141
	global_store_dwordx2 v[154:155], v[156:157], off offset:1536
	v_pk_fma_f32 v[154:155], v[0:1], v[150:151], 0 op_sel_hi:[1,0,0]
	v_pk_fma_f32 v[156:157], v[2:3], v[150:151], 0 op_sel_hi:[1,0,0]
	v_pk_fma_f32 v[158:159], v[4:5], v[150:151], 0 op_sel_hi:[1,0,0]
	v_pk_fma_f32 v[160:161], v[6:7], v[150:151], 0 op_sel_hi:[1,0,0]
	v_pk_fma_f32 v[154:155], v[12:13], v[150:151], v[154:155] op_sel:[0,1,0]
	v_pk_fma_f32 v[156:157], v[14:15], v[150:151], v[156:157] op_sel:[0,1,0]
	v_pk_fma_f32 v[160:161], v[10:11], v[150:151], v[160:161] op_sel:[0,1,0]
	v_pk_fma_f32 v[150:151], v[8:9], v[150:151], v[158:159] op_sel:[0,1,0]
	v_pk_fma_f32 v[154:155], v[20:21], v[152:153], v[154:155] op_sel_hi:[1,0,1]
	v_mov_b32_e32 v96, v153
	v_pk_fma_f32 v[156:157], v[22:23], v[152:153], v[156:157] op_sel_hi:[1,0,1]
	v_pk_fma_f32 v[150:151], v[16:17], v[152:153], v[150:151] op_sel_hi:[1,0,1]
	v_pk_fma_f32 v[158:159], v[18:19], v[152:153], v[160:161] op_sel_hi:[1,0,1]
	v_pk_fma_f32 v[154:155], v[28:29], v[96:97], v[154:155] op_sel_hi:[1,0,1]
	v_pk_fma_f32 v[152:153], v[30:31], v[96:97], v[156:157] op_sel_hi:[1,0,1]
	v_pk_fma_f32 v[156:157], v[26:27], v[96:97], v[158:159] op_sel_hi:[1,0,1]
	v_pk_fma_f32 v[150:151], v[24:25], v[96:97], v[150:151] op_sel_hi:[1,0,1]
	v_pk_fma_f32 v[154:155], v[36:37], v[146:147], v[154:155] op_sel_hi:[1,0,1]
	v_pk_fma_f32 v[152:153], v[38:39], v[146:147], v[152:153] op_sel_hi:[1,0,1]
	v_pk_fma_f32 v[150:151], v[32:33], v[146:147], v[150:151] op_sel_hi:[1,0,1]
	v_pk_fma_f32 v[156:157], v[34:35], v[146:147], v[156:157] op_sel_hi:[1,0,1]
	v_pk_fma_f32 v[154:155], v[44:45], v[146:147], v[154:155] op_sel:[0,1,0]
	v_pk_fma_f32 v[152:153], v[46:47], v[146:147], v[152:153] op_sel:[0,1,0]
	v_pk_fma_f32 v[156:157], v[42:43], v[146:147], v[156:157] op_sel:[0,1,0]
	v_pk_fma_f32 v[146:147], v[40:41], v[146:147], v[150:151] op_sel:[0,1,0]
	v_pk_fma_f32 v[150:151], v[52:53], v[148:149], v[154:155] op_sel_hi:[1,0,1]
	v_mov_b32_e32 v96, v149
	v_pk_fma_f32 v[152:153], v[54:55], v[148:149], v[152:153] op_sel_hi:[1,0,1]
	v_pk_fma_f32 v[146:147], v[48:49], v[148:149], v[146:147] op_sel_hi:[1,0,1]
	v_pk_fma_f32 v[154:155], v[50:51], v[148:149], v[156:157] op_sel_hi:[1,0,1]
	v_pk_fma_f32 v[150:151], v[60:61], v[96:97], v[150:151] op_sel_hi:[1,0,1]
	v_pk_fma_f32 v[148:149], v[62:63], v[96:97], v[152:153] op_sel_hi:[1,0,1]
	v_pk_fma_f32 v[152:153], v[58:59], v[96:97], v[154:155] op_sel_hi:[1,0,1]
	v_pk_fma_f32 v[146:147], v[56:57], v[96:97], v[146:147] op_sel_hi:[1,0,1]
	v_pk_fma_f32 v[150:151], v[68:69], v[142:143], v[150:151] op_sel_hi:[1,0,1]
	v_pk_fma_f32 v[148:149], v[70:71], v[142:143], v[148:149] op_sel_hi:[1,0,1]
	v_pk_fma_f32 v[146:147], v[64:65], v[142:143], v[146:147] op_sel_hi:[1,0,1]
	v_pk_fma_f32 v[152:153], v[66:67], v[142:143], v[152:153] op_sel_hi:[1,0,1]
	v_pk_fma_f32 v[150:151], v[76:77], v[142:143], v[150:151] op_sel:[0,1,0]
	v_pk_fma_f32 v[148:149], v[78:79], v[142:143], v[148:149] op_sel:[0,1,0]
	v_pk_fma_f32 v[152:153], v[74:75], v[142:143], v[152:153] op_sel:[0,1,0]
	v_pk_fma_f32 v[142:143], v[72:73], v[142:143], v[146:147] op_sel:[0,1,0]
	v_pk_fma_f32 v[146:147], v[92:93], v[144:145], v[150:151] op_sel_hi:[1,0,1]
	v_mov_b32_e32 v96, v145
	v_pk_fma_f32 v[148:149], v[94:95], v[144:145], v[148:149] op_sel_hi:[1,0,1]
	v_pk_fma_f32 v[142:143], v[88:89], v[144:145], v[142:143] op_sel_hi:[1,0,1]
	v_pk_fma_f32 v[150:151], v[90:91], v[144:145], v[152:153] op_sel_hi:[1,0,1]
	v_pk_fma_f32 v[146:147], v[102:103], v[96:97], v[146:147] op_sel_hi:[1,0,1]
	v_pk_fma_f32 v[144:145], v[104:105], v[96:97], v[148:149] op_sel_hi:[1,0,1]
	v_pk_fma_f32 v[148:149], v[100:101], v[96:97], v[150:151] op_sel_hi:[1,0,1]
	v_pk_fma_f32 v[142:143], v[98:99], v[96:97], v[142:143] op_sel_hi:[1,0,1]
	v_pk_fma_f32 v[146:147], v[110:111], v[138:139], v[146:147] op_sel_hi:[1,0,1]
	v_pk_fma_f32 v[144:145], v[112:113], v[138:139], v[144:145] op_sel_hi:[1,0,1]
	v_pk_fma_f32 v[142:143], v[106:107], v[138:139], v[142:143] op_sel_hi:[1,0,1]
	v_pk_fma_f32 v[148:149], v[108:109], v[138:139], v[148:149] op_sel_hi:[1,0,1]
	v_pk_fma_f32 v[146:147], v[118:119], v[138:139], v[146:147] op_sel:[0,1,0]
	v_pk_fma_f32 v[144:145], v[120:121], v[138:139], v[144:145] op_sel:[0,1,0]
	v_pk_fma_f32 v[148:149], v[116:117], v[138:139], v[148:149] op_sel:[0,1,0]
	v_pk_fma_f32 v[138:139], v[114:115], v[138:139], v[142:143] op_sel:[0,1,0]
	v_pk_fma_f32 v[142:143], v[126:127], v[140:141], v[146:147] op_sel_hi:[1,0,1]
	v_mov_b32_e32 v96, v141
	v_pk_fma_f32 v[144:145], v[128:129], v[140:141], v[144:145] op_sel_hi:[1,0,1]
	v_pk_fma_f32 v[138:139], v[122:123], v[140:141], v[138:139] op_sel_hi:[1,0,1]
	v_pk_fma_f32 v[146:147], v[124:125], v[140:141], v[148:149] op_sel_hi:[1,0,1]
	v_pk_fma_f32 v[142:143], v[134:135], v[96:97], v[142:143] op_sel_hi:[1,0,1]
	v_pk_fma_f32 v[140:141], v[136:137], v[96:97], v[144:145] op_sel_hi:[1,0,1]
	v_pk_fma_f32 v[144:145], v[132:133], v[96:97], v[146:147] op_sel_hi:[1,0,1]
; __device__ __forceinline__ void phase_rows(const Ctx& c, int l) {
;     ...
;             float f[8];
; #pragma unroll
;             for (int h = 0; h < 4; ++h) { f[h] = wave_sum(a0[h]) + bfv[h]; f[4 + h] = wave_sum(a1[h]) + bfv[4 + h]; }
;             if (lane == 0) { *(f32x4*)(flog + (size_t)m * 8) = (f32x4){f[0], f[1], f[2], f[3]}; *(f32x4*)(flog + (size_t)m * 8 + 4) = (f32x4){f[4], f[5], f[6], f[7]}; }
	v_pk_fma_f32 v[138:139], v[130:131], v[96:97], v[138:139] op_sel_hi:[1,0,1]
	v_add_f32_dpp v96, v142, v142 quad_perm:[1,0,3,2] row_mask:0xf bank_mask:0xf bound_ctrl:1
	s_nop 1
	v_add_f32_dpp v96, v96, v96 quad_perm:[2,3,0,1] row_mask:0xf bank_mask:0xf bound_ctrl:1
	s_nop 1
	v_add_f32_dpp v96, v96, v96 row_half_mirror row_mask:0xf bank_mask:0xf bound_ctrl:1
	s_nop 1
	v_add_f32_dpp v96, v96, v96 row_mirror row_mask:0xf bank_mask:0xf bound_ctrl:1
	s_nop 0
	v_readlane_b32 s62, v96, 0
	v_readlane_b32 s21, v96, 16
	v_readlane_b32 s46, v96, 32
	v_readlane_b32 s17, v96, 48
	v_add_f32_dpp v96, v138, v138 quad_perm:[1,0,3,2] row_mask:0xf bank_mask:0xf bound_ctrl:1
	s_nop 1
	v_add_f32_dpp v96, v96, v96 quad_perm:[2,3,0,1] row_mask:0xf bank_mask:0xf bound_ctrl:1
	s_nop 1
	v_add_f32_dpp v96, v96, v96 row_half_mirror row_mask:0xf bank_mask:0xf bound_ctrl:1
	s_nop 1
	v_add_f32_dpp v96, v96, v96 row_mirror row_mask:0xf bank_mask:0xf bound_ctrl:1
	s_nop 0
	v_readlane_b32 s42, v96, 0
	v_readlane_b32 s6, v96, 16
	v_readlane_b32 s40, v96, 32
	v_readlane_b32 s0, v96, 48
	v_add_f32_dpp v96, v143, v143 quad_perm:[1,0,3,2] row_mask:0xf bank_mask:0xf bound_ctrl:1
	s_nop 1
	v_add_f32_dpp v96, v96, v96 quad_perm:[2,3,0,1] row_mask:0xf bank_mask:0xf bound_ctrl:1
	s_nop 1
	v_add_f32_dpp v96, v96, v96 row_half_mirror row_mask:0xf bank_mask:0xf bound_ctrl:1
	s_nop 1
	v_add_f32_dpp v96, v96, v96 row_mirror row_mask:0xf bank_mask:0xf bound_ctrl:1
	s_nop 0
	v_readlane_b32 s63, v96, 0
	v_readlane_b32 s72, v96, 16
	v_readlane_b32 s47, v96, 32
	v_readlane_b32 s34, v96, 48
	v_add_f32_dpp v96, v139, v139 quad_perm:[1,0,3,2] row_mask:0xf bank_mask:0xf bound_ctrl:1
	s_nop 1
	v_add_f32_dpp v96, v96, v96 quad_perm:[2,3,0,1] row_mask:0xf bank_mask:0xf bound_ctrl:1
	s_nop 1
	v_add_f32_dpp v96, v96, v96 row_half_mirror row_mask:0xf bank_mask:0xf bound_ctrl:1
	s_nop 1
	v_add_f32_dpp v96, v96, v96 row_mirror row_mask:0xf bank_mask:0xf bound_ctrl:1
	s_nop 0
	v_readlane_b32 s43, v96, 0
	v_readlane_b32 s20, v96, 16
	v_readlane_b32 s41, v96, 32
	v_readlane_b32 s16, v96, 48
	v_add_f32_dpp v96, v140, v140 quad_perm:[1,0,3,2] row_mask:0xf bank_mask:0xf bound_ctrl:1
	s_nop 1
	v_add_f32_dpp v96, v96, v96 quad_perm:[2,3,0,1] row_mask:0xf bank_mask:0xf bound_ctrl:1
	s_nop 1
	v_add_f32_dpp v96, v96, v96 row_half_mirror row_mask:0xf bank_mask:0xf bound_ctrl:1
	s_nop 1
	v_add_f32_dpp v96, v96, v96 row_mirror row_mask:0xf bank_mask:0xf bound_ctrl:1
	s_nop 0
	v_readlane_b32 s70, v96, 0
	v_readlane_b32 s80, v96, 16
	v_readlane_b32 s68, v96, 32
	v_readlane_b32 s74, v96, 48
	v_add_f32_dpp v96, v144, v144 quad_perm:[1,0,3,2] row_mask:0xf bank_mask:0xf bound_ctrl:1
	s_nop 1
	v_add_f32_dpp v96, v96, v96 quad_perm:[2,3,0,1] row_mask:0xf bank_mask:0xf bound_ctrl:1
	s_nop 1
	v_add_f32_dpp v96, v96, v96 row_half_mirror row_mask:0xf bank_mask:0xf bound_ctrl:1
	s_nop 1
	v_add_f32_dpp v96, v96, v96 row_mirror row_mask:0xf bank_mask:0xf bound_ctrl:1
	s_nop 0
	v_readlane_b32 s66, v96, 0
	v_readlane_b32 s36, v96, 16
	v_readlane_b32 s64, v96, 32
	v_readlane_b32 s31, v96, 48
	v_add_f32_dpp v96, v141, v141 quad_perm:[1,0,3,2] row_mask:0xf bank_mask:0xf bound_ctrl:1
	s_nop 1
	v_add_f32_dpp v96, v96, v96 quad_perm:[2,3,0,1] row_mask:0xf bank_mask:0xf bound_ctrl:1
	s_nop 1
	v_add_f32_dpp v96, v96, v96 row_half_mirror row_mask:0xf bank_mask:0xf bound_ctrl:1
	s_nop 1
	v_add_f32_dpp v96, v96, v96 row_mirror row_mask:0xf bank_mask:0xf bound_ctrl:1
	s_nop 0
	v_readlane_b32 s71, v96, 0
	v_readlane_b32 s86, v96, 16
	v_readlane_b32 s69, v96, 32
	v_readlane_b32 s81, v96, 48
	v_add_f32_dpp v96, v145, v145 quad_perm:[1,0,3,2] row_mask:0xf bank_mask:0xf bound_ctrl:1
	s_nop 1
	v_add_f32_dpp v96, v96, v96 quad_perm:[2,3,0,1] row_mask:0xf bank_mask:0xf bound_ctrl:1
	s_nop 1
	v_add_f32_dpp v96, v96, v96 row_half_mirror row_mask:0xf bank_mask:0xf bound_ctrl:1
	s_nop 1
	v_add_f32_dpp v96, v96, v96 row_mirror row_mask:0xf bank_mask:0xf bound_ctrl:1
	s_nop 0
	v_readlane_b32 s67, v96, 0
	v_readlane_b32 s75, v96, 16
	v_readlane_b32 s65, v96, 32
	v_readlane_b32 s73, v96, 48
	s_and_saveexec_b64 s[60:61], s[38:39]
	s_cbranch_execz .LBB0_485
	v_mov_b32_e32 v138, s80
	v_mov_b32_e32 v139, s86
	v_mov_b32_e32 v140, s21
	v_mov_b32_e32 v141, s72
	v_mov_b32_e32 v142, s74
	v_mov_b32_e32 v143, s81
	v_mov_b32_e32 v144, s17
	v_mov_b32_e32 v145, s34
	v_pk_add_f32 v[138:139], s[70:71], v[138:139]
	v_pk_add_f32 v[140:141], s[62:63], v[140:141]
	v_pk_add_f32 v[142:143], s[68:69], v[142:143]
	v_pk_add_f32 v[144:145], s[46:47], v[144:145]
	v_pk_add_f32 v[138:139], v[138:139], v[142:143]
	v_pk_add_f32 v[144:145], v[140:141], v[144:145]
	v_pk_add_f32 v[140:141], v[86:87], v[138:139]
	v_pk_add_f32 v[138:139], v[84:85], v[144:145]
	v_mov_b32_e32 v142, s36
	v_mov_b32_e32 v143, s75
	v_mov_b32_e32 v144, s6
	v_mov_b32_e32 v145, s20
	v_mov_b32_e32 v146, s31
	v_mov_b32_e32 v147, s73
	v_mov_b32_e32 v148, s0
	v_mov_b32_e32 v149, s16
	s_lshl_b64 s[16:17], s[54:55], 5
	v_readlane_b32 s0, v253, 25
	v_pk_add_f32 v[142:143], s[66:67], v[142:143]
	v_pk_add_f32 v[144:145], s[42:43], v[144:145]
	v_pk_add_f32 v[146:147], s[64:65], v[146:147]
	v_pk_add_f32 v[148:149], s[40:41], v[148:149]
	s_add_u32 s16, s0, s16
	v_readlane_b32 s0, v253, 26
	v_pk_add_f32 v[148:149], v[144:145], v[148:149]
	v_pk_add_f32 v[142:143], v[142:143], v[146:147]
	s_addc_u32 s17, s0, s17
	v_pk_add_f32 v[144:145], v[82:83], v[142:143]
	v_pk_add_f32 v[142:143], v[80:81], v[148:149]
	global_store_dwordx4 v97, v[138:141], s[16:17]
	global_store_dwordx4 v97, v[142:145], s[16:17] offset:16
	s_branch .LBB0_485
